# lnpass inside phase 6 as before, scan workgroups' y rows stored write-through so their arrival needs no L2 write-back
# speedup vs baseline: 1.0110x; 1.0073x over previous
; #define LAS __attribute__((address_space(3)))
; __device__ __forceinline__ bf16_t f2bf(float f) { return (bf16_t)(pk2(f, 0.f) & 0xffffu); }
; __device__ __forceinline__ void scan_unit(const Ctx& p, int chain, int rq, LAS unsigned char* lds) {
;     ...
;         auto issue = [&](HReg& R, int c) {
;             const int row = row0 + c * SCH + tt, rp = row > 0 ? row - 1 : 0;
;             R.zr = *(const u32x2*)(ZRW + (size_t)row * SHW + c0); R.zrp = *(const u32x2*)(ZRW + (size_t)rp * SHW + c0);
;             R.zk = *(const u32x2*)(ZRW + (size_t)row * SHW + 512 + c0); R.zkp = *(const u32x2*)(ZRW + (size_t)rp * SHW + 512 + c0);
;             R.ab = *(const u32x2*)(AB + (size_t)row * 512 + c0); R.dec = *(const f32x4*)(DEC + (size_t)row * 512 + c0);
;             R.zv = (u32x2){0u, 0u}; R.zvp = (u32x2){0u, 0u};
;             if (hasv) { R.zv = *(const u32x2*)(ZRW + (size_t)row * SHW + 1024 + vc0); R.zvp = *(const u32x2*)(ZRW + (size_t)rp * SHW + 1024 + vc0); }
;     ...
;         auto yout = [&](int c) {
;             const LAS float* Y = YB + (c & 1) * YP_F + (tt * 16 + cg4) * 16;
;             const f32x4 y0 = *(const LAS f32x4*)Y, y1 = *(const LAS f32x4*)(Y + 4), y2 = *(const LAS f32x4*)(Y + 8), y3 = *(const LAS f32x4*)(Y + 12);
;             const f32x4 ys = (y0 + y1) + (y2 + y3);
;             ORW[(size_t)(row0 + c * SCH + tt) * 512 + h * 64 + 16 * rq + cg4] = f2bf((ys[0] + ys[1]) + (ys[2] + ys[3]));
;         };
.LBB0_1733:
	s_or_b64 exec, exec, s[12:13]
	v_lshlrev_b32_e32 v85, 6, v78
	v_add_u32_e32 v31, v67, v77
	v_add_u32_e32 v84, v31, v85
	s_waitcnt lgkmcnt(0)
	s_barrier
	ds_read_b128 v[70:73], v84 offset:43008
	ds_read_b128 v[86:89], v84 offset:43024
	ds_read_b128 v[90:93], v84 offset:43040
	ds_read_b128 v[94:97], v84 offset:43056
	s_and_b32 s10, s17, 48
	s_lshl_b32 s12, s16, 1
	s_add_u32 s12, s4, s12
	s_waitcnt lgkmcnt(2)
	v_pk_add_f32 v[72:73], v[72:73], v[88:89]
	v_pk_add_f32 v[70:71], v[70:71], v[86:87]
	s_waitcnt lgkmcnt(0)
	v_pk_add_f32 v[86:87], v[92:93], v[96:97]
	v_pk_add_f32 v[88:89], v[90:91], v[94:95]
	s_addc_u32 s13, s5, 0
	s_lshl_b32 s10, s10, 1
	v_pk_add_f32 v[72:73], v[72:73], v[86:87]
	v_pk_add_f32 v[70:71], v[70:71], v[88:89]
	s_add_u32 s12, s12, s10
	v_pk_mov_b32 v[86:87], v[70:71], v[72:73] op_sel:[1,0]
	v_mov_b32_e32 v71, v73
	s_addc_u32 s13, s13, 0
	v_lshlrev_b32_e32 v50, 1, v78
	v_pk_add_f32 v[70:71], v[86:87], v[70:71]
	v_add_u32_e32 v72, 0x50, v66
	v_lshl_add_u64 v[80:81], s[12:13], 0, v[50:51]
	v_add_f32_e32 v31, v70, v71
	v_ashrrev_i32_e32 v73, 31, v72
	v_cvt_pk_bf16_f32 v31, v31, s0
	v_lshl_add_u64 v[68:69], v[80:81], 0, v[68:69]
	v_add_u32_e32 v78, 64, v66
	v_lshlrev_b64 v[66:67], 11, v[72:73]
	global_store_short v[68:69], v31, off sc1
	v_lshl_or_b32 v66, v75, 2, v66
	s_mov_b64 s[12:13], 0xfd20000
	v_lshlrev_b64 v[68:69], 10, v[72:73]
	v_lshl_add_u64 v[66:67], v[66:67], 0, s[12:13]
	v_or_b32_e32 v68, v68, v28
	s_mov_b64 s[12:13], 0x3200000
	v_mov_b32_e32 v31, v51
	v_lshl_add_u64 v[68:69], v[68:69], 0, s[12:13]
	v_mad_i64_i32 v[70:71], s[12:13], v72, s20, v[30:31]
	s_lshl_b32 s10, s28, 17
	v_ashrrev_i32_e32 v75, 31, v74
	s_mov_b64 s[12:13], 0x8340800
	s_and_b32 s10, s10, 0xc00000
	v_lshlrev_b64 v[74:75], 10, v[74:75]
	v_lshl_add_u64 v[70:71], v[70:71], 0, s[12:13]
	v_mad_i64_i32 v[72:73], s[12:13], v72, s20, v[28:29]
	v_lshl_add_u64 v[74:75], s[10:11], 0, v[74:75]
	s_lshl_b32 s10, s28, 5
	s_and_b32 s12, s10, 0x380
	v_ashrrev_i32_e32 v77, 31, v76
	v_or_b32_e32 v29, s12, v74
	s_and_b32 s13, s10, 0x60
	v_lshlrev_b64 v[76:77], 10, v[76:77]
	v_or3_b32 v74, v29, s13, v50
	s_mov_b64 s[10:11], 0x8000
	v_or_b32_e32 v29, s12, v76
	s_mov_b32 s21, 2
	v_lshl_add_u64 v[74:75], v[74:75], 0, s[10:11]
	v_or3_b32 v76, v29, s13, v50
	v_add_u32_e32 v85, v79, v85
	s_mov_b64 s[12:13], 0x10000
	s_mov_b64 s[14:15], 0x1c000
	v_mov_b32_e32 v50, v78
	s_branch .LBB0_1737

; #define LAS __attribute__((address_space(3)))
; __device__ __forceinline__ bf16_t f2bf(float f) { return (bf16_t)(pk2(f, 0.f) & 0xffffu); }
; __device__ __forceinline__ void scan_unit(const Ctx& p, int chain, int rq, LAS unsigned char* lds) {
;     ...
;         auto yout = [&](int c) {
;             const LAS float* Y = YB + (c & 1) * YP_F + (tt * 16 + cg4) * 16;
;             const f32x4 y0 = *(const LAS f32x4*)Y, y1 = *(const LAS f32x4*)(Y + 4), y2 = *(const LAS f32x4*)(Y + 8), y3 = *(const LAS f32x4*)(Y + 12);
;             const f32x4 ys = (y0 + y1) + (y2 + y3);
;             ORW[(size_t)(row0 + c * SCH + tt) * 512 + h * 64 + 16 * rq + cg4] = f2bf((ys[0] + ys[1]) + (ys[2] + ys[3]));
;         };
.LBB0_1735:
	s_waitcnt lgkmcnt(0)
	s_barrier
	ds_read_b128 v[78:81], v84 offset:43008
	ds_read_b128 v[86:89], v84 offset:43024
	ds_read_b128 v[90:93], v84 offset:43040
	ds_read_b128 v[94:97], v84 offset:43056
	s_waitcnt lgkmcnt(2)
	v_pk_add_f32 v[80:81], v[80:81], v[88:89]
	v_pk_add_f32 v[78:79], v[78:79], v[86:87]
	s_waitcnt lgkmcnt(0)
	v_pk_add_f32 v[86:87], v[92:93], v[96:97]
	v_pk_add_f32 v[88:89], v[90:91], v[94:95]
	v_pk_add_f32 v[80:81], v[80:81], v[86:87]
	v_pk_add_f32 v[78:79], v[78:79], v[88:89]
	s_nop 0
	v_pk_mov_b32 v[86:87], v[78:79], v[80:81] op_sel:[1,0]
	v_mov_b32_e32 v79, v81
	v_pk_add_f32 v[78:79], v[86:87], v[78:79]
	s_nop 0
	v_add_f32_e32 v29, v78, v79
	v_cvt_pk_bf16_f32 v29, v29, s0
	v_lshl_add_u64 v[78:79], s[4:5], 0, v[74:75]
	global_store_short v[78:79], v29, off sc1

; __device__ __forceinline__ void scan_unit(const Ctx& p, int chain, int rq, LAS unsigned char* lds) {
;     ...
;         auto commit = [&](const HReg& R, int c) {
;             float zr[4], pr[4], zk[4], pk[4], a[4], zv[4], pv[4];
;             unpack4(R.zr, zr); unpack4(R.zrp, pr); unpack4(R.zk, zk); unpack4(R.zkp, pk); unpack4(R.ab, a); unpack4(R.zv, zv); unpack4(R.zvp, pv);
;             if (c == 0 && tt == 0) {
; #pragma unroll
;                 for (int e = 0; e < 4; ++e) { pr[e] = 0.f; pk[e] = 0.f; pv[e] = 0.f; }
;                 if (smp) { const float* s0 = p.in(5) + (size_t)cb * SHW;
; #pragma unroll
;                     for (int e = 0; e < 4; ++e) { pr[e] = s0[c0 + e]; pk[e] = s0[512 + c0 + e]; pv[e] = s0[1024 + vc0 + e]; } }
;             }
;             float r[4], k[4], kk[4], n2 = 0.f;
; #pragma unroll
;             for (int e = 0; e < 4; ++e) { r[e] = zr[e] + (pr[e] - zr[e]) * mur[e]; k[e] = zk[e] + (pk[e] - zk[e]) * muk[e]; kk[e] = k[e] * kkc[e]; n2 += kk[e] * kk[e]; }
;             n2 = sum16(n2);
;             const float inv = __builtin_amdgcn_rsqf(fmaxf(n2, 1e-24f));
;             float ka[4], kp[4];
; #pragma unroll
;             for (int e = 0; e < 4; ++e) { kk[e] *= inv; ka[e] = kk[e] * a[e]; kp[e] = k[e] * (1.f + (a[e] - 1.f) * kac[e]); }
;             LAS float* OP = B0 + (c & 1) * SBUF_F + tt * 320 + 4 * cg4;
;             *(LAS f32x4*)(OP) = R.dec;
;             *(LAS f32x4*)(OP + 64) = (f32x4){kk[0], kk[1], kk[2], kk[3]};
;             *(LAS f32x4*)(OP + 128) = (f32x4){ka[0], ka[1], ka[2], ka[3]};
;             *(LAS f32x4*)(OP + 192) = (f32x4){kp[0], kp[1], kp[2], kp[3]};
;             *(LAS f32x4*)(OP + 256) = (f32x4){r[0], r[1], r[2], r[3]};
;             if (hasv) { LAS float* VW = B0 + (c & 1) * SBUF_F + SCH * 320 + (4 * cg4) * 16 + tt;
; #pragma unroll
;                 for (int e = 0; e < 4; ++e) VW[e * 16] = zv[e] + (pv[e] - zv[e]) * muv[e]; }
;         };
;         auto yout = [&](int c) {
;             const LAS float* Y = YB + (c & 1) * YP_F + (tt * 16 + cg4) * 16;
;             const f32x4 y0 = *(const LAS f32x4*)Y, y1 = *(const LAS f32x4*)(Y + 4), y2 = *(const LAS f32x4*)(Y + 8), y3 = *(const LAS f32x4*)(Y + 12);
;             const f32x4 ys = (y0 + y1) + (y2 + y3);
;             ORW[(size_t)(row0 + c * SCH + tt) * 512 + h * 64 + 16 * rq + cg4] = f2bf((ys[0] + ys[1]) + (ys[2] + ys[3]));
;         };
.LBB0_1744:
	s_waitcnt lgkmcnt(0)
	s_barrier
	ds_read_b128 v[78:81], v85 offset:59392
	ds_read_b128 v[86:89], v85 offset:59408
	ds_read_b128 v[90:93], v85 offset:59424
	ds_read_b128 v[94:97], v85 offset:59440
	s_andn2_b64 vcc, exec, s[16:17]
	s_waitcnt lgkmcnt(2)
	v_pk_add_f32 v[80:81], v[80:81], v[88:89]
	v_pk_add_f32 v[78:79], v[78:79], v[86:87]
	s_waitcnt lgkmcnt(0)
	v_pk_add_f32 v[86:87], v[92:93], v[96:97]
	v_pk_add_f32 v[88:89], v[90:91], v[94:95]
	v_pk_add_f32 v[80:81], v[80:81], v[86:87]
	v_pk_add_f32 v[78:79], v[78:79], v[88:89]
	s_nop 0
	v_pk_mov_b32 v[86:87], v[78:79], v[80:81] op_sel:[1,0]
	v_mov_b32_e32 v79, v81
	v_pk_add_f32 v[78:79], v[86:87], v[78:79]
	s_nop 0
	v_add_f32_e32 v29, v78, v79
	v_cvt_pk_bf16_f32 v29, v29, s0
	v_lshl_add_u64 v[78:79], s[4:5], 0, v[76:77]
	global_store_short v[78:79], v29, off sc1
	s_cbranch_vccnz .LBB0_1736
	s_waitcnt vmcnt(4)
	v_lshlrev_b32_e32 v88, 16, v56
	v_and_b32_e32 v89, 0xffff0000, v56
	v_lshlrev_b32_e32 v90, 16, v58
	v_and_b32_e32 v91, 0xffff0000, v58
	v_pk_add_f32 v[90:91], v[90:91], v[88:89] neg_lo:[0,1] neg_hi:[0,1]
	v_lshlrev_b32_e32 v94, 16, v57
	v_and_b32_e32 v95, 0xffff0000, v57
	v_lshlrev_b32_e32 v96, 16, v59
	v_and_b32_e32 v97, 0xffff0000, v59
	v_pk_fma_f32 v[90:91], v[4:5], v[90:91], v[88:89]
	v_pk_add_f32 v[96:97], v[96:97], v[94:95] neg_lo:[0,1] neg_hi:[0,1]
	v_pk_mul_f32 v[88:89], v[8:9], v[90:91]
	v_pk_fma_f32 v[94:95], v[6:7], v[96:97], v[94:95]
	v_pk_mul_f32 v[92:93], v[88:89], v[88:89]
	v_pk_mul_f32 v[96:97], v[10:11], v[94:95]
	v_add_f32_e32 v29, v92, v93
	v_pk_mul_f32 v[98:99], v[96:97], v[96:97]
	v_lshlrev_b32_e32 v78, 16, v52
	v_add_f32_e32 v29, v98, v29
	v_add_f32_e32 v29, v99, v29
	v_and_b32_e32 v79, 0xffff0000, v52
	v_lshlrev_b32_e32 v80, 16, v54
	v_add_f32_dpp v29, v29, v29 quad_perm:[1,0,3,2] row_mask:0xf bank_mask:0xf bound_ctrl:1
	v_and_b32_e32 v81, 0xffff0000, v54
	v_pk_add_f32 v[80:81], v[80:81], v[78:79] neg_lo:[0,1] neg_hi:[0,1]
	v_add_f32_dpp v29, v29, v29 quad_perm:[2,3,0,1] row_mask:0xf bank_mask:0xf bound_ctrl:1
	v_pk_fma_f32 v[78:79], v[0:1], v[80:81], v[78:79]
	v_lshlrev_b32_e32 v80, 16, v53
	v_add_f32_dpp v29, v29, v29 row_half_mirror row_mask:0xf bank_mask:0xf bound_ctrl:1
	v_and_b32_e32 v81, 0xffff0000, v53
	v_lshlrev_b32_e32 v86, 16, v55
	v_add_f32_dpp v29, v29, v29 row_mirror row_mask:0xf bank_mask:0xf bound_ctrl:1
	v_max_f32_e32 v29, 0x179abe15, v29
	v_rsq_f32_e32 v92, v29
	v_and_b32_e32 v87, 0xffff0000, v55
	v_pk_add_f32 v[86:87], v[86:87], v[80:81] neg_lo:[0,1] neg_hi:[0,1]
	s_waitcnt vmcnt(3)
	v_lshlrev_b32_e32 v98, 16, v60
	v_pk_fma_f32 v[80:81], v[2:3], v[86:87], v[80:81]
	v_pk_mul_f32 v[86:87], v[88:89], v[92:93] op_sel_hi:[1,0]
	v_and_b32_e32 v99, 0xffff0000, v60
	v_pk_mul_f32 v[88:89], v[96:97], v[92:93] op_sel_hi:[1,0]
	v_lshlrev_b32_e32 v92, 16, v61
	v_and_b32_e32 v93, 0xffff0000, v61
	s_waitcnt vmcnt(2)
	ds_write_b128 v82, v[24:27] offset:21504
	ds_write_b128 v82, v[86:89] offset:21760
	v_pk_mul_f32 v[86:87], v[86:87], v[98:99]
	v_pk_mul_f32 v[88:89], v[88:89], v[92:93]
	ds_write_b128 v82, v[86:89] offset:22016
	v_pk_add_f32 v[86:87], v[92:93], -1.0 op_sel_hi:[1,0]
	v_pk_add_f32 v[88:89], v[98:99], -1.0 op_sel_hi:[1,0]
	v_pk_fma_f32 v[86:87], v[14:15], v[86:87], 1.0 op_sel_hi:[1,1,0]
	v_pk_fma_f32 v[92:93], v[12:13], v[88:89], 1.0 op_sel_hi:[1,1,0]
	v_pk_mul_f32 v[88:89], v[94:95], v[86:87]
	v_pk_mul_f32 v[86:87], v[90:91], v[92:93]
	ds_write_b128 v82, v[86:89] offset:22272
	ds_write_b128 v82, v[78:81] offset:22528
	s_and_saveexec_b64 s[16:17], s[2:3]
	s_cbranch_execz .LBB0_1747
	v_and_b32_e32 v29, 0xffff0000, v65
	v_lshlrev_b32_e32 v31, 16, v65
	v_and_b32_e32 v78, 0xffff0000, v64
	v_lshlrev_b32_e32 v79, 16, v64
	v_and_b32_e32 v80, 0xffff0000, v63
	v_lshlrev_b32_e32 v81, 16, v63
	v_and_b32_e32 v86, 0xffff0000, v62
	v_lshlrev_b32_e32 v87, 16, v62
	v_sub_f32_e32 v79, v79, v87
	v_sub_f32_e32 v78, v78, v86
	v_sub_f32_e32 v31, v31, v81
	v_sub_f32_e32 v29, v29, v80
	v_fmac_f32_e32 v87, v16, v79
	v_fmac_f32_e32 v86, v17, v78
	v_add_u32_e32 v78, 0xa400, v83
	v_fmac_f32_e32 v81, v18, v31
	v_fmac_f32_e32 v80, v19, v29
	ds_write2_b32 v78, v87, v86 offset1:16
	ds_write2_b32 v78, v81, v80 offset0:32 offset1:48

;     __device__ __forceinline__ unsigned char* ws() const { return (unsigned char*)ptr(37); }
; #define ws (p.ws())
; __device__ __forceinline__ void sub_barrier(const Ctx& p, unsigned n) {
;     asm volatile("s_waitcnt vmcnt(0)" ::: "memory");
;     __syncthreads();
;     if (threadIdx.x == 0) {
;         unsigned* c = (unsigned*)(p.ws() + WS_CTR) + 128;
;         __builtin_amdgcn_fence(__ATOMIC_RELEASE, "agent");
;         asm volatile("s_waitcnt vmcnt(0)" ::: "memory");
;         __hip_atomic_fetch_add(c, 1u, __ATOMIC_RELAXED, __HIP_MEMORY_SCOPE_AGENT);
.Lscan_ffn2w:
	s_waitcnt vmcnt(0) lgkmcnt(0)
	s_barrier
	v_cmp_eq_u32_e32 vcc, 0, v180
	s_and_saveexec_b64 s[2:3], vcc
	s_cbranch_execz .Lln_sa
	v_mov_b32_e32 v0, 0x23528
	ds_read_b64 v[0:1], v0
	s_waitcnt lgkmcnt(0)
	v_readfirstlane_b32 s4, v0
	v_readfirstlane_b32 s5, v1
	s_nop 4
	s_add_u32 s4, s4, 0x3180300
	s_addc_u32 s5, s5, 0
	s_waitcnt vmcnt(0)
	v_mov_b32_e32 v0, 0
	v_mov_b32_e32 v1, 1
	global_atomic_add v0, v1, s[4:5]
